# conv module: FIR weights/bias and LayerNorm gain/bias loaded once per layer into persistent registers instead of per tile / per row
# speedup vs baseline: 1.0063x; 1.0063x over previous
.LBB7_803:
	s_or_b64 exec, exec, s[6:7]
	v_readlane_b32 s4, v252, 7
	v_readlane_b32 s5, v252, 8
	s_andn2_b64 vcc, exec, s[4:5]
	s_cbranch_vccnz .LBB7_813
	s_load_dwordx8 s[12:19], s[42:43], 0xa0
	v_readlane_b32 s4, v250, 10
	v_readlane_b32 s5, v250, 11
	s_lshl_b64 s[4:5], s[4:5], 2
	v_readlane_b32 s3, v250, 27
	s_waitcnt lgkmcnt(0)
	s_add_u32 s6, s18, s4
	s_addc_u32 s7, s19, s5
	s_add_u32 s8, s16, s4
	s_addc_u32 s9, s17, s5
	s_add_u32 s12, s12, s3
	s_movk_i32 s3, 0xba0
	s_addc_u32 s13, s13, 0
	v_cmp_gt_i32_e32 vcc, s3, v150
	s_movk_i32 s3, 0x180
	s_add_u32 s4, s14, s4
	v_cmp_gt_i32_e64 s[40:41], s3, v150
	v_ashrrev_i32_e32 v151, 31, v150
	v_lshlrev_b32_e32 v0, 2, v150
	v_readlane_b32 s3, v253, 39
	s_addc_u32 s5, s15, s5
	v_lshlrev_b64 v[2:3], 2, v[150:151]
	v_add_u32_e32 v108, 0, v0
	v_add_u32_e32 v109, s3, v0
	v_mov_b32_e32 v0, s3
	v_lshl_add_u64 v[10:11], s[4:5], 0, v[2:3]
	v_mad_u64_u32 v[12:13], s[4:5], v204, 24, v[0:1]
	v_lshl_add_u64 v[14:15], s[12:13], 0, v[2:3]
	s_mov_b64 s[4:5], 0x1200
	v_lshl_add_u64 v[16:17], v[14:15], 0, s[4:5]
	s_mov_b64 s[4:5], 0x1800
	v_lshl_add_u64 v[18:19], v[14:15], 0, s[4:5]
	s_mov_b64 s[4:5], 0x1e00
	v_lshl_add_u64 v[20:21], v[14:15], 0, s[4:5]
	s_mov_b64 s[4:5], 0x2400
	v_lshl_add_u64 v[22:23], v[14:15], 0, s[4:5]
	s_mov_b64 s[4:5], 0x2a00
	v_lshl_add_u64 v[24:25], v[14:15], 0, s[4:5]
	s_mov_b64 s[4:5], 0x3000
	v_lshl_add_u64 v[26:27], v[14:15], 0, s[4:5]
	s_mov_b64 s[4:5], 0x3600
	v_and_b32_e32 v0, 64, v163
	v_lshl_add_u64 v[28:29], v[14:15], 0, s[4:5]
	s_mov_b64 s[4:5], 0x3c00
	v_add_u32_e32 v0, 64, v0
	v_xor_b32_e32 v4, 1, v163
	v_lshl_add_u64 v[30:31], v[14:15], 0, s[4:5]
	s_mov_b64 s[4:5], 0x4200
	v_cmp_lt_i32_e64 s[42:43], v4, v0
	v_lshl_add_u64 v[32:33], v[14:15], 0, s[4:5]
	s_mov_b64 s[4:5], 0x4800
	v_cndmask_b32_e64 v4, v163, v4, s[42:43]
	v_lshl_add_u64 v[34:35], v[14:15], 0, s[4:5]
	s_mov_b64 s[4:5], 0x4e00
	v_lshlrev_b32_e32 v13, 2, v4
	v_xor_b32_e32 v4, 2, v163
	v_lshl_add_u64 v[36:37], v[14:15], 0, s[4:5]
	s_mov_b64 s[4:5], 0x5400
	v_cmp_lt_i32_e64 s[42:43], v4, v0
	v_lshl_add_u64 v[38:39], v[14:15], 0, s[4:5]
	s_mov_b64 s[4:5], 0x5a00
	v_cndmask_b32_e64 v4, v163, v4, s[42:43]
	v_lshl_add_u64 v[40:41], v[14:15], 0, s[4:5]
	s_mov_b64 s[4:5], 0x6000
	v_lshlrev_b32_e32 v110, 2, v4
	v_xor_b32_e32 v4, 4, v163
	v_lshl_add_u64 v[42:43], v[14:15], 0, s[4:5]
	s_mov_b64 s[4:5], 0x6600
	v_cmp_lt_i32_e64 s[42:43], v4, v0
	v_lshl_add_u64 v[44:45], v[14:15], 0, s[4:5]
	s_mov_b64 s[4:5], 0x6c00
	v_cndmask_b32_e64 v4, v163, v4, s[42:43]
	v_lshl_add_u64 v[46:47], v[14:15], 0, s[4:5]
	s_mov_b64 s[4:5], 0x7200
	v_lshlrev_b32_e32 v111, 2, v4
	v_xor_b32_e32 v4, 8, v163
	v_lshl_add_u64 v[48:49], v[14:15], 0, s[4:5]
	s_mov_b64 s[4:5], 0x7800
	v_cmp_lt_i32_e64 s[42:43], v4, v0
	v_lshl_add_u64 v[50:51], v[14:15], 0, s[4:5]
	s_mov_b64 s[4:5], 0x7e00
	v_cndmask_b32_e64 v4, v163, v4, s[42:43]
	v_lshl_add_u64 v[52:53], v[14:15], 0, s[4:5]
	s_mov_b64 s[4:5], 0x8400
	v_lshlrev_b32_e32 v112, 2, v4
	v_xor_b32_e32 v4, 16, v163
	v_lshl_add_u64 v[54:55], v[14:15], 0, s[4:5]
	s_mov_b64 s[4:5], 0x8a00
	v_cmp_lt_i32_e64 s[42:43], v4, v0
	v_lshl_add_u64 v[56:57], v[14:15], 0, s[4:5]
	s_mov_b64 s[4:5], 0x9000
	v_cndmask_b32_e64 v4, v163, v4, s[42:43]
	v_lshl_add_u64 v[58:59], v[14:15], 0, s[4:5]
	s_mov_b64 s[4:5], 0x9600
	v_lshlrev_b32_e32 v113, 2, v4
	v_xor_b32_e32 v4, 32, v163
	v_lshl_add_u64 v[60:61], v[14:15], 0, s[4:5]
	s_mov_b64 s[4:5], 0x9c00
	v_cmp_lt_i32_e64 s[42:43], v4, v0
	v_lshl_add_u64 v[62:63], v[14:15], 0, s[4:5]
	s_mov_b64 s[4:5], 0xa200
	v_cndmask_b32_e64 v0, v163, v4, s[42:43]
	v_mul_lo_u32 v4, v204, 6
	v_lshl_add_u64 v[64:65], v[14:15], 0, s[4:5]
	s_mov_b64 s[4:5], 0xa800
	v_ashrrev_i32_e32 v5, 31, v4
	v_lshl_add_u64 v[66:67], v[14:15], 0, s[4:5]
	s_mov_b64 s[4:5], 0xae00
	v_lshl_add_u64 v[68:69], v[14:15], 0, s[4:5]
	s_mov_b64 s[4:5], 0xb400
	v_lshlrev_b64 v[2:3], 2, v[4:5]
	v_lshlrev_b32_e32 v114, 2, v0
	v_lshl_add_u64 v[70:71], v[14:15], 0, s[4:5]
	v_add_u32_e32 v115, 0x10200, v108
	v_add_u32_e32 v116, 0x10800, v108
	v_add_u32_e32 v117, 0x10e00, v108
	v_add_u32_e32 v118, 0x11400, v108
	v_add_u32_e32 v119, 0x11a00, v108
	v_add_u32_e32 v120, 0x12000, v108
	v_add_u32_e32 v121, 0x12600, v108
	v_add_u32_e32 v122, 0x12c00, v108
	v_add_u32_e32 v123, 0x13200, v108
	v_add_u32_e32 v124, 0x13800, v108
	v_add_u32_e32 v125, 0x13e00, v108
	v_add_u32_e32 v126, 0x14400, v108
	v_add_u32_e32 v127, 0x14a00, v108
	v_add_u32_e32 v128, 0x15000, v108
	v_add_u32_e32 v129, 0x15600, v108
	v_add_u32_e32 v130, 0x15c00, v108
	v_add_u32_e32 v131, 0x16200, v108
	v_add_u32_e32 v132, 0x16800, v108
	v_add_u32_e32 v133, 0x16e00, v108
	v_lshl_add_u64 v[72:73], s[8:9], 0, v[2:3]
	v_lshl_add_u64 v[74:75], s[6:7], 0, v[2:3]
	v_lshl_add_u64 v[76:77], v[4:5], 1, s[0:1]
	s_and_saveexec_b64 s[4:5], s[40:41]
	global_load_dword v247, v[10:11], off
	global_load_dword v216, v[14:15], off
	global_load_dword v217, v[14:15], off offset:1536
	global_load_dword v218, v[14:15], off offset:3072
	global_load_dword v219, v[16:17], off
	global_load_dword v220, v[18:19], off
	global_load_dword v221, v[20:21], off
	global_load_dword v222, v[22:23], off
	global_load_dword v223, v[24:25], off
	global_load_dword v224, v[26:27], off
	global_load_dword v225, v[28:29], off
	global_load_dword v226, v[30:31], off
	global_load_dword v227, v[32:33], off
	global_load_dword v228, v[34:35], off
	global_load_dword v229, v[36:37], off
	global_load_dword v230, v[38:39], off
	global_load_dword v231, v[40:41], off
	global_load_dword v232, v[42:43], off
	global_load_dword v233, v[44:45], off
	global_load_dword v234, v[46:47], off
	global_load_dword v235, v[48:49], off
	global_load_dword v236, v[50:51], off
	global_load_dword v237, v[52:53], off
	global_load_dword v238, v[54:55], off
	global_load_dword v239, v[56:57], off
	global_load_dword v240, v[58:59], off
	global_load_dword v241, v[60:61], off
	global_load_dword v242, v[62:63], off
	global_load_dword v243, v[64:65], off
	global_load_dword v244, v[66:67], off
	global_load_dword v245, v[68:69], off
	global_load_dword v246, v[70:71], off
	s_or_b64 exec, exec, s[4:5]
	s_waitcnt vmcnt(0)
	global_load_dwordx4 v[20:23], v[72:73], off
	global_load_dwordx2 v[24:25], v[72:73], off offset:16
	global_load_dwordx4 v[28:31], v[74:75], off
	global_load_dwordx2 v[32:33], v[74:75], off offset:16
	s_waitcnt vmcnt(0)
	s_mov_b32 s12, s2
	s_branch .LBB7_806
.LBB7_805:
	s_or_b64 exec, exec, s[0:1]
	v_add_u32_e32 v0, s31, v12
	s_waitcnt lgkmcnt(0)
	s_barrier
	ds_read2_b64 v[2:5], v0 offset1:1
	s_add_i32 s0, s13, s86
	s_ashr_i32 s1, s0, 31
	s_lshl_b64 s[0:1], s[0:1], 11
	s_add_i32 s12, s12, s60
	s_waitcnt lgkmcnt(0)
	v_add_f32_e32 v6, 0, v2
	v_add_f32_e32 v8, v6, v3
	ds_read_b64 v[6:7], v0 offset:16
	v_add_f32_e32 v0, v8, v4
	v_add_f32_e32 v0, v0, v5
	s_waitcnt lgkmcnt(0)
	v_add_f32_e32 v0, v0, v6
	v_add_f32_e32 v0, v0, v7
	s_nop 0
	s_waitcnt lgkmcnt(0)
	s_nop 1
	v_add_f32_dpp v0, v0, v0 quad_perm:[1,0,3,2] row_mask:0xf bank_mask:0xf
	s_nop 0
	s_waitcnt lgkmcnt(0)
	s_nop 1
	v_add_f32_dpp v0, v0, v0 quad_perm:[2,3,0,1] row_mask:0xf bank_mask:0xf
	s_nop 0
	s_waitcnt lgkmcnt(0)
	s_nop 1
	v_add_f32_dpp v0, v0, v0 row_half_mirror row_mask:0xf bank_mask:0xf
	s_nop 0
	s_waitcnt lgkmcnt(0)
	s_nop 1
	v_add_f32_dpp v0, v0, v0 row_mirror row_mask:0xf bank_mask:0xf
	v_mov_b32_e32 v8, v0
	s_nop 1
	v_permlane16_swap_b32_e32 v0, v8
	s_waitcnt lgkmcnt(0)
	v_add_f32_e32 v0, v0, v8
	v_mov_b32_e32 v8, v0
	s_nop 1
	v_permlane32_swap_b32_e32 v0, v8
	s_waitcnt lgkmcnt(0)
	v_add_f32_e32 v8, v0, v8
	v_mul_f32_e32 v0, 0x3b2aaaab, v8
	v_fmac_f32_e32 v3, 0xbb2aaaab, v8
	v_fmamk_f32 v2, v8, 0xbb2aaaab, v2
	v_mul_f32_e32 v78, v3, v3
	v_pk_add_f32 v[8:9], v[4:5], v[0:1] op_sel_hi:[1,0] neg_lo:[0,1] neg_hi:[0,1]
	v_fmac_f32_e32 v78, v2, v2
	v_pk_mul_f32 v[4:5], v[8:9], v[8:9]
	v_pk_add_f32 v[82:83], v[6:7], v[0:1] op_sel_hi:[1,0] neg_lo:[0,1] neg_hi:[0,1]
	v_add_f32_e32 v4, v4, v78
	v_add_f32_e32 v78, v5, v4
	v_pk_mul_f32 v[4:5], v[82:83], v[82:83]
	s_nop 0
	v_add_f32_e32 v0, v4, v78
	v_add_f32_e32 v0, v5, v0
	s_nop 0
	s_waitcnt lgkmcnt(0)
	s_nop 1
	v_add_f32_dpp v0, v0, v0 quad_perm:[1,0,3,2] row_mask:0xf bank_mask:0xf
	s_nop 0
	s_waitcnt lgkmcnt(0)
	s_nop 1
	v_add_f32_dpp v0, v0, v0 quad_perm:[2,3,0,1] row_mask:0xf bank_mask:0xf
	s_nop 0
	s_waitcnt lgkmcnt(0)
	s_nop 1
	v_add_f32_dpp v0, v0, v0 row_half_mirror row_mask:0xf bank_mask:0xf
	s_nop 0
	s_waitcnt lgkmcnt(0)
	s_nop 1
	v_add_f32_dpp v0, v0, v0 row_mirror row_mask:0xf bank_mask:0xf
	v_mov_b32_e32 v4, v0
	s_nop 1
	v_permlane16_swap_b32_e32 v0, v4
	s_waitcnt lgkmcnt(0)
	v_add_f32_e32 v0, v0, v4
	v_mov_b32_e32 v4, v0
	s_nop 1
	v_permlane32_swap_b32_e32 v0, v4
	s_waitcnt lgkmcnt(0)
	v_add_f32_e32 v0, v0, v4
	v_fmamk_f32 v0, v0, 0x3b2aaaab, v162
	v_cmp_gt_f32_e64 s[42:43], s11, v0
	v_mul_f32_e32 v4, 0x4b800000, v0
	s_nop 0
	v_cndmask_b32_e64 v0, v0, v4, s[42:43]
	v_rsq_f32_e32 v0, v0
	s_nop 0
	v_mul_f32_e32 v4, 0x45800000, v0
	v_cndmask_b32_e64 v0, v0, v4, s[42:43]
	v_mul_f32_e32 v2, v2, v0
	v_fma_f32 v2, v20, v2, v28
	v_mul_f32_e32 v4, 0xbfb8aa3b, v2
	v_exp_f32_e32 v4, v4
	s_nop 0
	v_add_f32_e32 v4, 1.0, v4
	v_rcp_f32_e32 v4, v4
	s_nop 0
	v_mul_f32_e32 v4, v2, v4
	v_mul_f32_e32 v2, v3, v0
	v_fma_f32 v2, v21, v2, v29
	v_mul_f32_e32 v3, 0xbfb8aa3b, v2
	v_exp_f32_e32 v3, v3
	s_nop 0
	v_add_f32_e32 v3, 1.0, v3
	v_rcp_f32_e32 v3, v3
	s_nop 0
	v_mul_f32_e32 v5, v2, v3
	v_mul_f32_e32 v2, v8, v0
	v_fma_f32 v2, v22, v2, v30
	v_mul_f32_e32 v3, 0xbfb8aa3b, v2
	v_exp_f32_e32 v3, v3
	v_cvt_pk_bf16_f32 v4, v4, v5
	s_nop 0
	v_add_f32_e32 v3, 1.0, v3
	v_rcp_f32_e32 v3, v3
	s_nop 0
	v_mul_f32_e32 v6, v2, v3
	v_mul_f32_e32 v2, v9, v0
	v_fma_f32 v81, v23, v2, v31
	v_mul_f32_e32 v2, 0xbfb8aa3b, v81
	v_exp_f32_e32 v2, v2
	s_nop 0
	v_add_f32_e32 v2, 1.0, v2
	v_rcp_f32_e32 v2, v2
	s_nop 0
	v_mul_f32_e32 v7, v81, v2
	v_mul_f32_e32 v2, v82, v0
	v_mul_f32_e32 v0, v83, v0
	v_fma_f32 v2, v24, v2, v32
	v_fma_f32 v87, v25, v0, v33
	v_mul_f32_e32 v3, 0xbfb8aa3b, v2
	v_mul_f32_e32 v0, 0xbfb8aa3b, v87
	v_exp_f32_e32 v3, v3
	v_exp_f32_e32 v0, v0
	v_add_f32_e32 v3, 1.0, v3
	v_add_f32_e32 v0, 1.0, v0
	v_rcp_f32_e32 v3, v3
	v_rcp_f32_e32 v0, v0
	v_mul_f32_e32 v8, v2, v3
	v_mul_f32_e32 v0, v87, v0
	v_lshl_add_u64 v[2:3], v[76:77], 0, s[0:1]
	global_store_dword v[2:3], v4, off offset:1280
	v_cvt_pk_bf16_f32 v4, v6, v7
	global_store_dword v[2:3], v4, off offset:1284
	v_cvt_pk_bf16_f32 v0, v8, v0
	s_mul_i32 s0, s91, 0x600
	global_store_dword v[2:3], v0, off offset:1288
	v_add_u32_e32 v0, s0, v12
	ds_read2_b64 v[2:5], v0 offset1:1
	s_add_i32 s0, s13, s91
	s_ashr_i32 s1, s0, 31
	s_lshl_b64 s[0:1], s[0:1], 11
	s_waitcnt lgkmcnt(0)
	v_add_f32_e32 v6, 0, v2
	v_add_f32_e32 v8, v6, v3
	ds_read_b64 v[6:7], v0 offset:16
	v_add_f32_e32 v8, v8, v4
	v_add_f32_e32 v8, v8, v5
	s_waitcnt lgkmcnt(0)
	v_add_f32_e32 v8, v8, v6
	v_add_f32_e32 v8, v8, v7
	s_nop 0
	s_waitcnt lgkmcnt(0)
	s_nop 1
	v_add_f32_dpp v8, v8, v8 quad_perm:[1,0,3,2] row_mask:0xf bank_mask:0xf
	s_nop 0
	s_waitcnt lgkmcnt(0)
	s_nop 1
	v_add_f32_dpp v8, v8, v8 quad_perm:[2,3,0,1] row_mask:0xf bank_mask:0xf
	s_nop 0
	s_waitcnt lgkmcnt(0)
	s_nop 1
	v_add_f32_dpp v8, v8, v8 row_half_mirror row_mask:0xf bank_mask:0xf
	s_nop 0
	s_waitcnt lgkmcnt(0)
	s_nop 1
	v_add_f32_dpp v8, v8, v8 row_mirror row_mask:0xf bank_mask:0xf
	v_mov_b32_e32 v9, v8
	s_nop 1
	v_permlane16_swap_b32_e32 v8, v9
	s_waitcnt lgkmcnt(0)
	v_add_f32_e32 v8, v8, v9
	v_mov_b32_e32 v9, v8
	s_nop 1
	v_permlane32_swap_b32_e32 v8, v9
	s_waitcnt lgkmcnt(0)
	v_add_f32_e32 v9, v8, v9
	v_fmac_f32_e32 v3, 0xbb2aaaab, v9
	v_mul_f32_e32 v8, 0x3b2aaaab, v9
	v_fmamk_f32 v2, v9, 0xbb2aaaab, v2
	v_mul_f32_e32 v9, v3, v3
	v_fmac_f32_e32 v9, v2, v2
	v_pk_add_f32 v[82:83], v[4:5], v[8:9] op_sel_hi:[1,0] neg_lo:[0,1] neg_hi:[0,1]
	s_nop 0
	v_pk_mul_f32 v[4:5], v[82:83], v[82:83]
	s_nop 0
	v_add_f32_e32 v4, v4, v9
	v_pk_add_f32 v[8:9], v[6:7], v[8:9] op_sel_hi:[1,0] neg_lo:[0,1] neg_hi:[0,1]
	v_add_f32_e32 v78, v5, v4
	v_pk_mul_f32 v[4:5], v[8:9], v[8:9]
	s_nop 0
	v_add_f32_e32 v4, v4, v78
	v_add_f32_e32 v4, v5, v4
	s_nop 0
	s_waitcnt lgkmcnt(0)
	s_nop 1
	v_add_f32_dpp v4, v4, v4 quad_perm:[1,0,3,2] row_mask:0xf bank_mask:0xf
	s_nop 0
	s_waitcnt lgkmcnt(0)
	s_nop 1
	v_add_f32_dpp v4, v4, v4 quad_perm:[2,3,0,1] row_mask:0xf bank_mask:0xf
	s_nop 0
	s_waitcnt lgkmcnt(0)
	s_nop 1
	v_add_f32_dpp v4, v4, v4 row_half_mirror row_mask:0xf bank_mask:0xf
	s_nop 0
	s_waitcnt lgkmcnt(0)
	s_nop 1
	v_add_f32_dpp v4, v4, v4 row_mirror row_mask:0xf bank_mask:0xf
	v_mov_b32_e32 v5, v4
	s_nop 1
	v_permlane16_swap_b32_e32 v4, v5
	s_waitcnt lgkmcnt(0)
	v_add_f32_e32 v4, v4, v5
	v_mov_b32_e32 v5, v4
	s_nop 1
	v_permlane32_swap_b32_e32 v4, v5
	s_waitcnt lgkmcnt(0)
	v_add_f32_e32 v4, v4, v5
	v_fmamk_f32 v4, v4, 0x3b2aaaab, v162
	v_cmp_gt_f32_e64 s[42:43], s11, v4
	v_mul_f32_e32 v5, 0x4b800000, v4
	s_nop 0
	v_cndmask_b32_e64 v4, v4, v5, s[42:43]
	v_rsq_f32_e32 v4, v4
	s_nop 0
	v_mul_f32_e32 v5, 0x45800000, v4
	v_cndmask_b32_e64 v88, v4, v5, s[42:43]
	v_mul_f32_e32 v2, v2, v88
	v_mul_f32_e32 v3, v3, v88
	v_fma_f32 v2, v20, v2, v28
	v_mul_f32_e32 v4, 0xbfb8aa3b, v2
	v_exp_f32_e32 v4, v4
	v_fma_f32 v3, v21, v3, v29
	v_add_f32_e32 v4, 1.0, v4
	v_rcp_f32_e32 v4, v4
	s_nop 0
	v_mul_f32_e32 v2, v2, v4
	v_mul_f32_e32 v4, 0xbfb8aa3b, v3
	v_exp_f32_e32 v4, v4
	s_nop 0
	v_add_f32_e32 v4, 1.0, v4
	v_rcp_f32_e32 v4, v4
	s_nop 0
	v_mul_f32_e32 v3, v3, v4
	v_mul_f32_e32 v4, v82, v88
	v_fma_f32 v4, v22, v4, v30
	v_mul_f32_e32 v5, 0xbfb8aa3b, v4
	v_exp_f32_e32 v5, v5
	v_mul_f32_e32 v6, v8, v88
	v_fma_f32 v6, v24, v6, v32
	v_cvt_pk_bf16_f32 v2, v2, v3
	v_add_f32_e32 v5, 1.0, v5
	v_rcp_f32_e32 v5, v5
	s_nop 0
	v_mul_f32_e32 v4, v4, v5
	v_mul_f32_e32 v5, v83, v88
	v_fma_f32 v81, v23, v5, v31
	v_mul_f32_e32 v7, 0xbfb8aa3b, v6
	v_exp_f32_e32 v7, v7
	v_mul_f32_e32 v5, 0xbfb8aa3b, v81
	v_exp_f32_e32 v5, v5
	v_add_f32_e32 v7, 1.0, v7
	v_rcp_f32_e32 v7, v7
	v_add_f32_e32 v5, 1.0, v5
	v_rcp_f32_e32 v5, v5
	v_mul_f32_e32 v6, v6, v7
	v_mul_f32_e32 v7, v9, v88
	v_fma_f32 v87, v25, v7, v33
	v_mul_f32_e32 v7, 0xbfb8aa3b, v87
	v_exp_f32_e32 v7, v7
	v_lshl_add_u64 v[8:9], v[76:77], 0, s[0:1]
	v_mul_f32_e32 v5, v81, v5
	global_store_dword v[8:9], v2, off offset:1280
	v_add_f32_e32 v7, 1.0, v7
	v_rcp_f32_e32 v7, v7
	v_cvt_pk_bf16_f32 v2, v4, v5
	global_store_dword v[8:9], v2, off offset:1284
	s_add_i32 s0, s13, s93
	v_mul_f32_e32 v7, v87, v7
	v_cvt_pk_bf16_f32 v2, v6, v7
	global_store_dword v[8:9], v2, off offset:1288
	ds_read2_b64 v[2:5], v0 offset0:192 offset1:193
	s_ashr_i32 s1, s0, 31
	s_lshl_b64 s[0:1], s[0:1], 11
	s_waitcnt lgkmcnt(0)
	v_add_f32_e32 v6, 0, v2
	v_add_f32_e32 v8, v6, v3
	ds_read_b64 v[6:7], v0 offset:1552
	v_add_f32_e32 v8, v8, v4
	v_add_f32_e32 v8, v8, v5
	s_waitcnt lgkmcnt(0)
	v_add_f32_e32 v8, v8, v6
	v_add_f32_e32 v8, v8, v7
	s_nop 0
	s_waitcnt lgkmcnt(0)
	s_nop 1
	v_add_f32_dpp v8, v8, v8 quad_perm:[1,0,3,2] row_mask:0xf bank_mask:0xf
	s_nop 0
	s_waitcnt lgkmcnt(0)
	s_nop 1
	v_add_f32_dpp v8, v8, v8 quad_perm:[2,3,0,1] row_mask:0xf bank_mask:0xf
	s_nop 0
	s_waitcnt lgkmcnt(0)
	s_nop 1
	v_add_f32_dpp v8, v8, v8 row_half_mirror row_mask:0xf bank_mask:0xf
	s_nop 0
	s_waitcnt lgkmcnt(0)
	s_nop 1
	v_add_f32_dpp v8, v8, v8 row_mirror row_mask:0xf bank_mask:0xf
	v_mov_b32_e32 v9, v8
	s_nop 1
	v_permlane16_swap_b32_e32 v8, v9
	s_waitcnt lgkmcnt(0)
	v_add_f32_e32 v8, v8, v9
	v_mov_b32_e32 v9, v8
	s_nop 1
	v_permlane32_swap_b32_e32 v8, v9
	s_waitcnt lgkmcnt(0)
	v_add_f32_e32 v9, v8, v9
	v_fmac_f32_e32 v3, 0xbb2aaaab, v9
	v_mul_f32_e32 v8, 0x3b2aaaab, v9
	v_fmamk_f32 v2, v9, 0xbb2aaaab, v2
	v_mul_f32_e32 v9, v3, v3
	v_fmac_f32_e32 v9, v2, v2
	v_pk_add_f32 v[82:83], v[4:5], v[8:9] op_sel_hi:[1,0] neg_lo:[0,1] neg_hi:[0,1]
	s_nop 0
	v_pk_mul_f32 v[4:5], v[82:83], v[82:83]
	s_nop 0
	v_add_f32_e32 v4, v4, v9
	v_pk_add_f32 v[8:9], v[6:7], v[8:9] op_sel_hi:[1,0] neg_lo:[0,1] neg_hi:[0,1]
	v_add_f32_e32 v78, v5, v4
	v_pk_mul_f32 v[4:5], v[8:9], v[8:9]
	s_nop 0
	v_add_f32_e32 v4, v4, v78
	v_add_f32_e32 v4, v5, v4
	s_nop 0
	s_waitcnt lgkmcnt(0)
	s_nop 1
	v_add_f32_dpp v4, v4, v4 quad_perm:[1,0,3,2] row_mask:0xf bank_mask:0xf
	s_nop 0
	s_waitcnt lgkmcnt(0)
	s_nop 1
	v_add_f32_dpp v4, v4, v4 quad_perm:[2,3,0,1] row_mask:0xf bank_mask:0xf
	s_nop 0
	s_waitcnt lgkmcnt(0)
	s_nop 1
	v_add_f32_dpp v4, v4, v4 row_half_mirror row_mask:0xf bank_mask:0xf
	s_nop 0
	s_waitcnt lgkmcnt(0)
	s_nop 1
	v_add_f32_dpp v4, v4, v4 row_mirror row_mask:0xf bank_mask:0xf
	v_mov_b32_e32 v5, v4
	s_nop 1
	v_permlane16_swap_b32_e32 v4, v5
	s_waitcnt lgkmcnt(0)
	v_add_f32_e32 v4, v4, v5
	v_mov_b32_e32 v5, v4
	s_nop 1
	v_permlane32_swap_b32_e32 v4, v5
	s_waitcnt lgkmcnt(0)
	v_add_f32_e32 v4, v4, v5
	v_fmamk_f32 v4, v4, 0x3b2aaaab, v162
	v_cmp_gt_f32_e64 s[42:43], s11, v4
	v_mul_f32_e32 v5, 0x4b800000, v4
	s_nop 0
	v_cndmask_b32_e64 v4, v4, v5, s[42:43]
	v_rsq_f32_e32 v4, v4
	s_nop 0
	v_mul_f32_e32 v5, 0x45800000, v4
	v_cndmask_b32_e64 v88, v4, v5, s[42:43]
	v_mul_f32_e32 v2, v2, v88
	v_fma_f32 v2, v20, v2, v28
	v_mul_f32_e32 v4, 0xbfb8aa3b, v2
	v_exp_f32_e32 v4, v4
	s_nop 0
	v_add_f32_e32 v4, 1.0, v4
	v_rcp_f32_e32 v4, v4
	s_nop 0
	v_mul_f32_e32 v4, v2, v4
	v_mul_f32_e32 v2, v3, v88
	v_fma_f32 v2, v21, v2, v29
	v_mul_f32_e32 v3, 0xbfb8aa3b, v2
	v_exp_f32_e32 v3, v3
	s_nop 0
	v_add_f32_e32 v3, 1.0, v3
	v_rcp_f32_e32 v3, v3
	s_nop 0
	v_mul_f32_e32 v5, v2, v3
	v_mul_f32_e32 v2, v82, v88
	v_fma_f32 v2, v22, v2, v30
	v_mul_f32_e32 v3, 0xbfb8aa3b, v2
	v_exp_f32_e32 v3, v3
	v_cvt_pk_bf16_f32 v4, v4, v5
	s_nop 0
	v_add_f32_e32 v3, 1.0, v3
	v_rcp_f32_e32 v3, v3
	s_nop 0
	v_mul_f32_e32 v6, v2, v3
	v_mul_f32_e32 v2, v83, v88
	v_fma_f32 v81, v23, v2, v31
	v_mul_f32_e32 v2, 0xbfb8aa3b, v81
	v_exp_f32_e32 v2, v2
	s_nop 0
	v_add_f32_e32 v2, 1.0, v2
	v_rcp_f32_e32 v2, v2
	s_nop 0
	v_mul_f32_e32 v7, v81, v2
	v_mul_f32_e32 v2, v8, v88
	v_fma_f32 v2, v24, v2, v32
	v_mul_f32_e32 v3, 0xbfb8aa3b, v2
	v_exp_f32_e32 v3, v3
	s_nop 0
	v_add_f32_e32 v3, 1.0, v3
	v_rcp_f32_e32 v3, v3
	s_nop 0
	v_mul_f32_e32 v8, v2, v3
	v_mul_f32_e32 v2, v9, v88
	v_fma_f32 v87, v25, v2, v33
	v_mul_f32_e32 v2, 0xbfb8aa3b, v87
	v_exp_f32_e32 v2, v2
	s_nop 0
	v_add_f32_e32 v2, 1.0, v2
	v_rcp_f32_e32 v2, v2
	s_nop 0
	v_mul_f32_e32 v9, v87, v2
	v_lshl_add_u64 v[2:3], v[76:77], 0, s[0:1]
	global_store_dword v[2:3], v4, off offset:1280
	v_cvt_pk_bf16_f32 v4, v6, v7
	global_store_dword v[2:3], v4, off offset:1284
	v_cvt_pk_bf16_f32 v4, v8, v9
	global_store_dword v[2:3], v4, off offset:1288
	v_add_u32_e32 v2, 0xc00, v0
	ds_read2_b64 v[2:5], v2 offset1:1
	s_add_i32 s0, s13, s28
	s_ashr_i32 s1, s0, 31
	s_lshl_b64 s[0:1], s[0:1], 11
	s_cmpk_lt_i32 s12, 0x400
	s_waitcnt lgkmcnt(0)
	v_add_f32_e32 v6, 0, v2
	v_add_f32_e32 v8, v6, v3
	ds_read_b64 v[6:7], v0 offset:3088
	v_add_f32_e32 v0, v8, v4
	v_add_f32_e32 v0, v0, v5
	s_waitcnt lgkmcnt(0)
	v_add_f32_e32 v0, v0, v6
	v_add_f32_e32 v0, v0, v7
	s_nop 0
	s_waitcnt lgkmcnt(0)
	s_nop 1
	v_add_f32_dpp v0, v0, v0 quad_perm:[1,0,3,2] row_mask:0xf bank_mask:0xf
	s_nop 0
	s_waitcnt lgkmcnt(0)
	s_nop 1
	v_add_f32_dpp v0, v0, v0 quad_perm:[2,3,0,1] row_mask:0xf bank_mask:0xf
	s_nop 0
	s_waitcnt lgkmcnt(0)
	s_nop 1
	v_add_f32_dpp v0, v0, v0 row_half_mirror row_mask:0xf bank_mask:0xf
	s_nop 0
	s_waitcnt lgkmcnt(0)
	s_nop 1
	v_add_f32_dpp v0, v0, v0 row_mirror row_mask:0xf bank_mask:0xf
	v_mov_b32_e32 v8, v0
	s_nop 1
	v_permlane16_swap_b32_e32 v0, v8
	s_waitcnt lgkmcnt(0)
	v_add_f32_e32 v0, v0, v8
	v_mov_b32_e32 v8, v0
	s_nop 1
	v_permlane32_swap_b32_e32 v0, v8
	s_waitcnt lgkmcnt(0)
	v_add_f32_e32 v8, v0, v8
	v_mul_f32_e32 v0, 0x3b2aaaab, v8
	v_fmac_f32_e32 v3, 0xbb2aaaab, v8
	v_fmamk_f32 v2, v8, 0xbb2aaaab, v2
	v_mul_f32_e32 v78, v3, v3
	v_pk_add_f32 v[8:9], v[4:5], v[0:1] op_sel_hi:[1,0] neg_lo:[0,1] neg_hi:[0,1]
	v_fmac_f32_e32 v78, v2, v2
	v_pk_mul_f32 v[4:5], v[8:9], v[8:9]
	v_pk_add_f32 v[82:83], v[6:7], v[0:1] op_sel_hi:[1,0] neg_lo:[0,1] neg_hi:[0,1]
	v_add_f32_e32 v4, v4, v78
	v_add_f32_e32 v78, v5, v4
	v_pk_mul_f32 v[4:5], v[82:83], v[82:83]
	s_nop 0
	v_add_f32_e32 v0, v4, v78
	v_add_f32_e32 v0, v5, v0
	s_nop 0
	s_waitcnt lgkmcnt(0)
	s_nop 1
	v_add_f32_dpp v0, v0, v0 quad_perm:[1,0,3,2] row_mask:0xf bank_mask:0xf
	s_nop 0
	s_waitcnt lgkmcnt(0)
	s_nop 1
	v_add_f32_dpp v0, v0, v0 quad_perm:[2,3,0,1] row_mask:0xf bank_mask:0xf
	s_nop 0
	s_waitcnt lgkmcnt(0)
	s_nop 1
	v_add_f32_dpp v0, v0, v0 row_half_mirror row_mask:0xf bank_mask:0xf
	s_nop 0
	s_waitcnt lgkmcnt(0)
	s_nop 1
	v_add_f32_dpp v0, v0, v0 row_mirror row_mask:0xf bank_mask:0xf
	v_mov_b32_e32 v4, v0
	s_nop 1
	v_permlane16_swap_b32_e32 v0, v4
	s_waitcnt lgkmcnt(0)
	v_add_f32_e32 v0, v0, v4
	v_mov_b32_e32 v4, v0
	s_nop 1
	v_permlane32_swap_b32_e32 v0, v4
	s_waitcnt lgkmcnt(0)
	v_add_f32_e32 v0, v0, v4
	v_fmamk_f32 v0, v0, 0x3b2aaaab, v162
	v_cmp_gt_f32_e64 s[42:43], s11, v0
	v_mul_f32_e32 v4, 0x4b800000, v0
	s_nop 0
	v_cndmask_b32_e64 v0, v0, v4, s[42:43]
	v_rsq_f32_e32 v0, v0
	s_nop 0
	v_mul_f32_e32 v4, 0x45800000, v0
	v_cndmask_b32_e64 v0, v0, v4, s[42:43]
	v_mul_f32_e32 v2, v2, v0
	v_fma_f32 v2, v20, v2, v28
	v_mul_f32_e32 v4, 0xbfb8aa3b, v2
	v_exp_f32_e32 v4, v4
	s_nop 0
	v_add_f32_e32 v4, 1.0, v4
	v_rcp_f32_e32 v4, v4
	s_nop 0
	v_mul_f32_e32 v4, v2, v4
	v_mul_f32_e32 v2, v3, v0
	v_fma_f32 v2, v21, v2, v29
	v_mul_f32_e32 v3, 0xbfb8aa3b, v2
	v_exp_f32_e32 v3, v3
	s_nop 0
	v_add_f32_e32 v3, 1.0, v3
	v_rcp_f32_e32 v3, v3
	s_nop 0
	v_mul_f32_e32 v5, v2, v3
	v_mul_f32_e32 v2, v8, v0
	v_fma_f32 v2, v22, v2, v30
	v_mul_f32_e32 v3, 0xbfb8aa3b, v2
	v_exp_f32_e32 v3, v3
	v_cvt_pk_bf16_f32 v4, v4, v5
	s_nop 0
	v_add_f32_e32 v3, 1.0, v3
	v_rcp_f32_e32 v3, v3
	s_nop 0
	v_mul_f32_e32 v6, v2, v3
	v_mul_f32_e32 v2, v9, v0
	v_fma_f32 v81, v23, v2, v31
	v_mul_f32_e32 v2, 0xbfb8aa3b, v81
	v_exp_f32_e32 v2, v2
	s_nop 0
	v_add_f32_e32 v2, 1.0, v2
	v_rcp_f32_e32 v2, v2
	s_nop 0
	v_mul_f32_e32 v7, v81, v2
	v_mul_f32_e32 v2, v82, v0
	v_mul_f32_e32 v0, v83, v0
	v_fma_f32 v2, v24, v2, v32
	v_fma_f32 v87, v25, v0, v33
	v_mul_f32_e32 v3, 0xbfb8aa3b, v2
	v_mul_f32_e32 v0, 0xbfb8aa3b, v87
	v_exp_f32_e32 v3, v3
	v_exp_f32_e32 v0, v0
	v_add_f32_e32 v3, 1.0, v3
	v_add_f32_e32 v0, 1.0, v0
	v_rcp_f32_e32 v3, v3
	v_rcp_f32_e32 v0, v0
	v_mul_f32_e32 v8, v2, v3
	v_mul_f32_e32 v0, v87, v0
	v_lshl_add_u64 v[2:3], v[76:77], 0, s[0:1]
	global_store_dword v[2:3], v4, off offset:1280
	v_cvt_pk_bf16_f32 v4, v6, v7
	global_store_dword v[2:3], v4, off offset:1284
	v_cvt_pk_bf16_f32 v0, v8, v0
	global_store_dword v[2:3], v0, off offset:1288
	s_cbranch_scc0 .LBB7_813

.LBB7_811:
	s_or_b64 exec, exec, s[0:1]
	s_waitcnt lgkmcnt(0)
	s_barrier
	s_and_saveexec_b64 s[0:1], s[40:41]
	s_cbranch_execz .LBB7_805
	ds_read2st64_b32 v[170:171], v108 offset1:6
	ds_read2st64_b32 v[172:173], v108 offset0:12 offset1:18
	ds_read2st64_b32 v[106:107], v108 offset0:24 offset1:30
	ds_read2st64_b32 v[104:105], v108 offset0:36 offset1:42
	ds_read2st64_b32 v[102:103], v108 offset0:48 offset1:54
	ds_read2st64_b32 v[100:101], v108 offset0:60 offset1:66
	ds_read2st64_b32 v[98:99], v108 offset0:72 offset1:78
	ds_read2st64_b32 v[96:97], v108 offset0:84 offset1:90
	ds_read2st64_b32 v[94:95], v108 offset0:96 offset1:102
	ds_read2st64_b32 v[92:93], v108 offset0:108 offset1:114
	ds_read2st64_b32 v[90:91], v108 offset0:120 offset1:126
	ds_read2st64_b32 v[88:89], v108 offset0:132 offset1:138
	ds_read2st64_b32 v[86:87], v108 offset0:144 offset1:150
	ds_read2st64_b32 v[84:85], v108 offset0:156 offset1:162
	ds_read2st64_b32 v[82:83], v108 offset0:168 offset1:174
	ds_read2st64_b32 v[80:81], v108 offset0:180 offset1:186
	ds_read2st64_b32 v[78:79], v108 offset0:192 offset1:198
	ds_read2st64_b32 v[8:9], v108 offset0:204 offset1:210
	ds_read2st64_b32 v[6:7], v108 offset0:216 offset1:222
	ds_read2st64_b32 v[4:5], v108 offset0:228 offset1:234
	ds_read2st64_b32 v[2:3], v108 offset0:240 offset1:246
	ds_read_b32 v178, v108 offset:64512
	s_waitcnt lgkmcnt(14)
	v_fma_f32 v170, v216, v170, v247
	v_fma_f32 v179, v216, v171, v247
	v_fmac_f32_e32 v170, v217, v171
	v_fmac_f32_e32 v179, v217, v172
	v_fmac_f32_e32 v170, v218, v172
	v_fmac_f32_e32 v179, v218, v173
	v_fmac_f32_e32 v170, v219, v173
	v_fmac_f32_e32 v179, v219, v106
	v_fmac_f32_e32 v170, v220, v106
	v_fmac_f32_e32 v179, v220, v107
	v_fmac_f32_e32 v170, v221, v107
	v_fmac_f32_e32 v179, v221, v104
	v_fmac_f32_e32 v170, v222, v104
	v_fmac_f32_e32 v179, v222, v105
	v_fmac_f32_e32 v170, v223, v105
	v_fmac_f32_e32 v179, v223, v102
	v_fmac_f32_e32 v170, v224, v102
	v_fmac_f32_e32 v179, v224, v103
	v_fmac_f32_e32 v170, v225, v103
	v_fmac_f32_e32 v179, v225, v100
	v_fmac_f32_e32 v170, v226, v100
	v_fmac_f32_e32 v179, v226, v101
	v_fmac_f32_e32 v170, v227, v101
	v_fmac_f32_e32 v179, v227, v98
	v_fmac_f32_e32 v170, v228, v98
	v_fmac_f32_e32 v179, v228, v99
	v_fmac_f32_e32 v170, v229, v99
	v_fmac_f32_e32 v179, v229, v96
	v_fmac_f32_e32 v170, v230, v96
	v_fmac_f32_e32 v179, v230, v97
	v_fmac_f32_e32 v170, v231, v97
	s_waitcnt lgkmcnt(13)
	v_fmac_f32_e32 v179, v231, v94
	v_fmac_f32_e32 v170, v232, v94
	v_fmac_f32_e32 v179, v232, v95
	v_fmac_f32_e32 v170, v233, v95
	s_waitcnt lgkmcnt(12)
	v_fmac_f32_e32 v179, v233, v92
	v_fmac_f32_e32 v170, v234, v92
	v_fmac_f32_e32 v179, v234, v93
	v_fmac_f32_e32 v170, v235, v93
	s_waitcnt lgkmcnt(11)
	v_fmac_f32_e32 v179, v235, v90
	v_fmac_f32_e32 v170, v236, v90
	v_fmac_f32_e32 v179, v236, v91
	v_fmac_f32_e32 v170, v237, v91
	s_waitcnt lgkmcnt(10)
	v_fmac_f32_e32 v179, v237, v88
	v_fmac_f32_e32 v170, v238, v88
	v_fmac_f32_e32 v179, v238, v89
	v_fmac_f32_e32 v170, v239, v89
	s_waitcnt lgkmcnt(9)
	v_fmac_f32_e32 v179, v239, v86
	v_fmac_f32_e32 v170, v240, v86
	v_fmac_f32_e32 v179, v240, v87
	v_fmac_f32_e32 v170, v241, v87
	s_waitcnt lgkmcnt(8)
	v_fmac_f32_e32 v179, v241, v84
	v_fmac_f32_e32 v170, v242, v84
	v_fmac_f32_e32 v179, v242, v85
	v_fmac_f32_e32 v170, v243, v85
	s_waitcnt lgkmcnt(7)
	v_fmac_f32_e32 v179, v243, v82
	v_fmac_f32_e32 v170, v244, v82
	v_fmac_f32_e32 v179, v244, v83
	v_fmac_f32_e32 v170, v245, v83
	s_waitcnt lgkmcnt(6)
	v_fmac_f32_e32 v179, v245, v80
	v_fmac_f32_e32 v170, v246, v80
	v_fmac_f32_e32 v179, v246, v81
	ds_write2st64_b32 v109, v170, v179 offset1:6
	v_fma_f32 v170, v216, v172, v247
	v_fmac_f32_e32 v170, v217, v173
	v_fma_f32 v171, v216, v173, v247
	v_fmac_f32_e32 v170, v218, v106
	v_fmac_f32_e32 v171, v217, v106
	v_fma_f32 v106, v216, v106, v247
	v_fmac_f32_e32 v170, v219, v107
	v_fmac_f32_e32 v171, v218, v107
	v_fmac_f32_e32 v106, v217, v107
	v_fma_f32 v107, v216, v107, v247
	v_fmac_f32_e32 v107, v217, v104
	v_fmac_f32_e32 v106, v218, v104
	v_fmac_f32_e32 v107, v218, v105
	v_fmac_f32_e32 v106, v219, v105
	v_fmac_f32_e32 v107, v219, v102
	v_fmac_f32_e32 v106, v220, v102
	v_fmac_f32_e32 v107, v220, v103
	v_fmac_f32_e32 v106, v221, v103
	v_fmac_f32_e32 v107, v221, v100
	v_fmac_f32_e32 v106, v222, v100
	v_fmac_f32_e32 v107, v222, v101
	v_fmac_f32_e32 v106, v223, v101
	v_fmac_f32_e32 v107, v223, v98
	v_fmac_f32_e32 v106, v224, v98
	v_fmac_f32_e32 v107, v224, v99
	v_fmac_f32_e32 v106, v225, v99
	v_fmac_f32_e32 v107, v225, v96
	v_fmac_f32_e32 v106, v226, v96
	v_fmac_f32_e32 v107, v226, v97
	v_fmac_f32_e32 v106, v227, v97
	v_fmac_f32_e32 v107, v227, v94
	v_fmac_f32_e32 v106, v228, v94
	v_fmac_f32_e32 v107, v228, v95
	v_fmac_f32_e32 v106, v229, v95
	v_fmac_f32_e32 v107, v229, v92
	v_fmac_f32_e32 v106, v230, v92
	v_fmac_f32_e32 v107, v230, v93
	v_fmac_f32_e32 v106, v231, v93
	v_fmac_f32_e32 v107, v231, v90
	v_fmac_f32_e32 v106, v232, v90
	v_fmac_f32_e32 v107, v232, v91
	v_fmac_f32_e32 v106, v233, v91
	v_fmac_f32_e32 v107, v233, v88
	v_fmac_f32_e32 v106, v234, v88
	v_fmac_f32_e32 v107, v234, v89
	v_fmac_f32_e32 v106, v235, v89
	v_fmac_f32_e32 v107, v235, v86
	v_fmac_f32_e32 v106, v236, v86
	v_fmac_f32_e32 v107, v236, v87
	v_fmac_f32_e32 v106, v237, v87
	v_fmac_f32_e32 v107, v237, v84
	v_fmac_f32_e32 v106, v238, v84
	v_fmac_f32_e32 v107, v238, v85
	v_fmac_f32_e32 v106, v239, v85
	v_fmac_f32_e32 v107, v239, v82
	v_fmac_f32_e32 v170, v220, v104
	v_fmac_f32_e32 v171, v219, v104
	v_fmac_f32_e32 v106, v240, v82
	v_fmac_f32_e32 v107, v240, v83
	v_fma_f32 v104, v216, v104, v247
	v_fmac_f32_e32 v170, v221, v105
	v_fmac_f32_e32 v171, v220, v105
	v_fmac_f32_e32 v106, v241, v83
	v_fmac_f32_e32 v107, v241, v80
	v_fmac_f32_e32 v104, v217, v105
	v_fma_f32 v105, v216, v105, v247
	v_fmac_f32_e32 v170, v222, v102
	v_fmac_f32_e32 v171, v221, v102
	v_fmac_f32_e32 v106, v242, v80
	v_fmac_f32_e32 v107, v242, v81
	v_fmac_f32_e32 v104, v218, v102
	v_fmac_f32_e32 v105, v217, v102
	v_fma_f32 v102, v216, v102, v247
	v_fmac_f32_e32 v170, v223, v103
	v_fmac_f32_e32 v171, v222, v103
	v_fmac_f32_e32 v106, v243, v81
	s_waitcnt lgkmcnt(6)
	v_fmac_f32_e32 v107, v243, v78
	v_fmac_f32_e32 v104, v219, v103
	v_fmac_f32_e32 v105, v218, v103
	v_fmac_f32_e32 v102, v217, v103
	v_fma_f32 v103, v216, v103, v247
	v_fmac_f32_e32 v170, v224, v100
	v_fmac_f32_e32 v171, v223, v100
	v_fmac_f32_e32 v106, v244, v78
	v_fmac_f32_e32 v107, v244, v79
	v_fmac_f32_e32 v104, v220, v100
	v_fmac_f32_e32 v105, v219, v100
	v_fmac_f32_e32 v102, v218, v100
	v_fmac_f32_e32 v103, v217, v100
	v_fma_f32 v100, v216, v100, v247
	v_fmac_f32_e32 v170, v225, v101
	v_fmac_f32_e32 v171, v224, v101
	v_fmac_f32_e32 v106, v245, v79
	s_waitcnt lgkmcnt(5)
	v_fmac_f32_e32 v107, v245, v8
	v_fmac_f32_e32 v104, v221, v101
	v_fmac_f32_e32 v105, v220, v101
	v_fmac_f32_e32 v102, v219, v101
	v_fmac_f32_e32 v103, v218, v101
	v_fmac_f32_e32 v100, v217, v101
	v_fma_f32 v101, v216, v101, v247
	v_fmac_f32_e32 v106, v246, v8
	v_fmac_f32_e32 v107, v246, v9
	v_fmac_f32_e32 v101, v217, v98
	v_fmac_f32_e32 v170, v226, v98
	v_fmac_f32_e32 v171, v225, v98
	ds_write2st64_b32 v109, v106, v107 offset0:24 offset1:30
	v_fmac_f32_e32 v104, v222, v98
	v_fmac_f32_e32 v105, v221, v98
	v_fmac_f32_e32 v102, v220, v98
	v_fmac_f32_e32 v103, v219, v98
	v_fmac_f32_e32 v100, v218, v98
	v_fmac_f32_e32 v101, v218, v99
	v_fma_f32 v106, v216, v98, v247
	v_fmac_f32_e32 v170, v227, v99
	v_fmac_f32_e32 v171, v226, v99
	v_fmac_f32_e32 v104, v223, v99
	v_fmac_f32_e32 v105, v222, v99
	v_fmac_f32_e32 v102, v221, v99
	v_fmac_f32_e32 v103, v220, v99
	v_fmac_f32_e32 v100, v219, v99
	v_fmac_f32_e32 v101, v219, v96
	v_fmac_f32_e32 v106, v217, v99
	v_fma_f32 v107, v216, v99, v247
	v_fmac_f32_e32 v170, v228, v96
	v_fmac_f32_e32 v171, v227, v96
	v_fmac_f32_e32 v104, v224, v96
	v_fmac_f32_e32 v105, v223, v96
	v_fmac_f32_e32 v102, v222, v96
	v_fmac_f32_e32 v103, v221, v96
	v_fmac_f32_e32 v100, v220, v96
	v_fmac_f32_e32 v101, v220, v97
	v_fmac_f32_e32 v106, v218, v96
	v_fmac_f32_e32 v107, v217, v96
	v_fma_f32 v96, v216, v96, v247
	v_fmac_f32_e32 v170, v229, v97
	v_fmac_f32_e32 v171, v228, v97
	v_fmac_f32_e32 v104, v225, v97
	v_fmac_f32_e32 v105, v224, v97
	v_fmac_f32_e32 v102, v223, v97
	v_fmac_f32_e32 v103, v222, v97
	v_fmac_f32_e32 v100, v221, v97
	v_fmac_f32_e32 v101, v221, v94
	v_fmac_f32_e32 v106, v219, v97
	v_fmac_f32_e32 v107, v218, v97
	v_fmac_f32_e32 v96, v217, v97
	v_fma_f32 v97, v216, v97, v247
	v_fmac_f32_e32 v170, v230, v94
	v_fmac_f32_e32 v171, v229, v94
	v_fmac_f32_e32 v104, v226, v94
	v_fmac_f32_e32 v105, v225, v94
	v_fmac_f32_e32 v102, v224, v94
	v_fmac_f32_e32 v103, v223, v94
	v_fmac_f32_e32 v100, v222, v94
	v_fmac_f32_e32 v101, v222, v95
	v_fmac_f32_e32 v106, v220, v94
	v_fmac_f32_e32 v107, v219, v94
	v_fmac_f32_e32 v96, v218, v94
	v_fmac_f32_e32 v97, v217, v94
	v_fma_f32 v94, v216, v94, v247
	v_fmac_f32_e32 v170, v231, v95
	v_fmac_f32_e32 v171, v230, v95
	v_fmac_f32_e32 v104, v227, v95
	v_fmac_f32_e32 v105, v226, v95
	v_fmac_f32_e32 v102, v225, v95
	v_fmac_f32_e32 v103, v224, v95
	v_fmac_f32_e32 v100, v223, v95
	v_fmac_f32_e32 v101, v223, v92
	v_fmac_f32_e32 v106, v221, v95
	v_fmac_f32_e32 v107, v220, v95
	v_fmac_f32_e32 v96, v219, v95
	v_fmac_f32_e32 v97, v218, v95
	v_fmac_f32_e32 v94, v217, v95
	v_fma_f32 v95, v216, v95, v247
	v_fmac_f32_e32 v170, v232, v92
	v_fmac_f32_e32 v171, v231, v92
	v_fmac_f32_e32 v104, v228, v92
	v_fmac_f32_e32 v105, v227, v92
	v_fmac_f32_e32 v102, v226, v92
	v_fmac_f32_e32 v103, v225, v92
	v_fmac_f32_e32 v100, v224, v92
	v_fmac_f32_e32 v101, v224, v93
	v_fmac_f32_e32 v106, v222, v92
	v_fmac_f32_e32 v107, v221, v92
	v_fmac_f32_e32 v96, v220, v92
	v_fmac_f32_e32 v97, v219, v92
	v_fmac_f32_e32 v94, v218, v92
	v_fmac_f32_e32 v95, v217, v92
	v_fma_f32 v92, v216, v92, v247
	v_fmac_f32_e32 v170, v233, v93
	v_fmac_f32_e32 v171, v232, v93
	v_fmac_f32_e32 v104, v229, v93
	v_fmac_f32_e32 v105, v228, v93
	v_fmac_f32_e32 v102, v227, v93
	v_fmac_f32_e32 v103, v226, v93
	v_fmac_f32_e32 v100, v225, v93
	v_fmac_f32_e32 v101, v225, v90
	v_fmac_f32_e32 v106, v223, v93
	v_fmac_f32_e32 v107, v222, v93
	v_fmac_f32_e32 v96, v221, v93
	v_fmac_f32_e32 v97, v220, v93
	v_fmac_f32_e32 v94, v219, v93
	v_fmac_f32_e32 v95, v218, v93
	v_fmac_f32_e32 v92, v217, v93
	v_fma_f32 v93, v216, v93, v247
	v_fmac_f32_e32 v170, v234, v90
	v_fmac_f32_e32 v171, v233, v90
	v_fmac_f32_e32 v104, v230, v90
	v_fmac_f32_e32 v105, v229, v90
	v_fmac_f32_e32 v102, v228, v90
	v_fmac_f32_e32 v103, v227, v90
	v_fmac_f32_e32 v100, v226, v90
	v_fmac_f32_e32 v101, v226, v91
	v_fmac_f32_e32 v106, v224, v90
	v_fmac_f32_e32 v107, v223, v90
	v_fmac_f32_e32 v96, v222, v90
	v_fmac_f32_e32 v97, v221, v90
	v_fmac_f32_e32 v94, v220, v90
	v_fmac_f32_e32 v95, v219, v90
	v_fmac_f32_e32 v92, v218, v90
	v_fmac_f32_e32 v93, v217, v90
	v_fma_f32 v90, v216, v90, v247
	v_fmac_f32_e32 v170, v235, v91
	v_fmac_f32_e32 v171, v234, v91
	v_fmac_f32_e32 v104, v231, v91
	v_fmac_f32_e32 v105, v230, v91
	v_fmac_f32_e32 v102, v229, v91
	v_fmac_f32_e32 v103, v228, v91
	v_fmac_f32_e32 v100, v227, v91
	v_fmac_f32_e32 v101, v227, v88
	v_fmac_f32_e32 v106, v225, v91
	v_fmac_f32_e32 v107, v224, v91
	v_fmac_f32_e32 v96, v223, v91
	v_fmac_f32_e32 v97, v222, v91
	v_fmac_f32_e32 v94, v221, v91
	v_fmac_f32_e32 v95, v220, v91
	v_fmac_f32_e32 v92, v219, v91
	v_fmac_f32_e32 v93, v218, v91
	v_fmac_f32_e32 v90, v217, v91
	v_fma_f32 v91, v216, v91, v247
	v_fmac_f32_e32 v170, v236, v88
	v_fmac_f32_e32 v171, v235, v88
	v_fmac_f32_e32 v104, v232, v88
	v_fmac_f32_e32 v105, v231, v88
	v_fmac_f32_e32 v102, v230, v88
	v_fmac_f32_e32 v103, v229, v88
	v_fmac_f32_e32 v100, v228, v88
	v_fmac_f32_e32 v101, v228, v89
	v_fmac_f32_e32 v106, v226, v88
	v_fmac_f32_e32 v107, v225, v88
	v_fmac_f32_e32 v96, v224, v88
	v_fmac_f32_e32 v97, v223, v88
	v_fmac_f32_e32 v94, v222, v88
	v_fmac_f32_e32 v95, v221, v88
	v_fmac_f32_e32 v92, v220, v88
	v_fmac_f32_e32 v93, v219, v88
	v_fmac_f32_e32 v90, v218, v88
	v_fmac_f32_e32 v91, v217, v88
	v_fma_f32 v88, v216, v88, v247
	v_fmac_f32_e32 v170, v237, v89
	v_fmac_f32_e32 v171, v236, v89
	v_fmac_f32_e32 v104, v233, v89
	v_fmac_f32_e32 v105, v232, v89
	v_fmac_f32_e32 v102, v231, v89
	v_fmac_f32_e32 v103, v230, v89
	v_fmac_f32_e32 v100, v229, v89
	v_fmac_f32_e32 v101, v229, v86
	v_fmac_f32_e32 v106, v227, v89
	v_fmac_f32_e32 v107, v226, v89
	v_fmac_f32_e32 v96, v225, v89
	v_fmac_f32_e32 v97, v224, v89
	v_fmac_f32_e32 v94, v223, v89
	v_fmac_f32_e32 v95, v222, v89
	v_fmac_f32_e32 v92, v221, v89
	v_fmac_f32_e32 v93, v220, v89
	v_fmac_f32_e32 v90, v219, v89
	v_fmac_f32_e32 v91, v218, v89
	v_fmac_f32_e32 v88, v217, v89
	v_fma_f32 v89, v216, v89, v247
	v_fmac_f32_e32 v170, v238, v86
	v_fmac_f32_e32 v171, v237, v86
	v_fmac_f32_e32 v104, v234, v86
	v_fmac_f32_e32 v105, v233, v86
	v_fmac_f32_e32 v102, v232, v86
	v_fmac_f32_e32 v103, v231, v86
	v_fmac_f32_e32 v100, v230, v86
	v_fmac_f32_e32 v101, v230, v87
	v_fmac_f32_e32 v106, v228, v86
	v_fmac_f32_e32 v107, v227, v86
	v_fmac_f32_e32 v96, v226, v86
	v_fmac_f32_e32 v97, v225, v86
	v_fmac_f32_e32 v94, v224, v86
	v_fmac_f32_e32 v95, v223, v86
	v_fmac_f32_e32 v92, v222, v86
	v_fmac_f32_e32 v93, v221, v86
	v_fmac_f32_e32 v90, v220, v86
	v_fmac_f32_e32 v91, v219, v86
	v_fmac_f32_e32 v88, v218, v86
	v_fmac_f32_e32 v89, v217, v86
	v_fma_f32 v86, v216, v86, v247
	v_fmac_f32_e32 v170, v239, v87
	v_fmac_f32_e32 v171, v238, v87
	v_fmac_f32_e32 v104, v235, v87
	v_fmac_f32_e32 v105, v234, v87
	v_fmac_f32_e32 v102, v233, v87
	v_fmac_f32_e32 v103, v232, v87
	v_fmac_f32_e32 v100, v231, v87
	v_fmac_f32_e32 v101, v231, v84
	v_fmac_f32_e32 v106, v229, v87
	v_fmac_f32_e32 v107, v228, v87
	v_fmac_f32_e32 v96, v227, v87
	v_fmac_f32_e32 v97, v226, v87
	v_fmac_f32_e32 v94, v225, v87
	v_fmac_f32_e32 v95, v224, v87
	v_fmac_f32_e32 v92, v223, v87
	v_fmac_f32_e32 v93, v222, v87
	v_fmac_f32_e32 v90, v221, v87
	v_fmac_f32_e32 v91, v220, v87
	v_fmac_f32_e32 v88, v219, v87
	v_fmac_f32_e32 v89, v218, v87
	v_fmac_f32_e32 v86, v217, v87
	v_fma_f32 v87, v216, v87, v247
	v_fmac_f32_e32 v170, v240, v84
	v_fmac_f32_e32 v171, v239, v84
	v_fmac_f32_e32 v104, v236, v84
	v_fmac_f32_e32 v105, v235, v84
	v_fmac_f32_e32 v102, v234, v84
	v_fmac_f32_e32 v103, v233, v84
	v_fmac_f32_e32 v100, v232, v84
	v_fmac_f32_e32 v101, v232, v85
	v_fmac_f32_e32 v106, v230, v84
	v_fmac_f32_e32 v107, v229, v84
	v_fmac_f32_e32 v96, v228, v84
	v_fmac_f32_e32 v97, v227, v84
	v_fmac_f32_e32 v94, v226, v84
	v_fmac_f32_e32 v95, v225, v84
	v_fmac_f32_e32 v92, v224, v84
	v_fmac_f32_e32 v93, v223, v84
	v_fmac_f32_e32 v90, v222, v84
	v_fmac_f32_e32 v91, v221, v84
	v_fmac_f32_e32 v88, v220, v84
	v_fmac_f32_e32 v89, v219, v84
	v_fmac_f32_e32 v86, v218, v84
	v_fmac_f32_e32 v87, v217, v84
	v_fma_f32 v84, v216, v84, v247
	v_fmac_f32_e32 v170, v241, v85
	v_fmac_f32_e32 v171, v240, v85
	v_fmac_f32_e32 v104, v237, v85
	v_fmac_f32_e32 v105, v236, v85
	v_fmac_f32_e32 v102, v235, v85
	v_fmac_f32_e32 v103, v234, v85
	v_fmac_f32_e32 v100, v233, v85
	v_fmac_f32_e32 v101, v233, v82
	v_fmac_f32_e32 v106, v231, v85
	v_fmac_f32_e32 v107, v230, v85
	v_fmac_f32_e32 v96, v229, v85
	v_fmac_f32_e32 v97, v228, v85
	v_fmac_f32_e32 v94, v227, v85
	v_fmac_f32_e32 v95, v226, v85
	v_fmac_f32_e32 v92, v225, v85
	v_fmac_f32_e32 v93, v224, v85
	v_fmac_f32_e32 v90, v223, v85
	v_fmac_f32_e32 v91, v222, v85
	v_fmac_f32_e32 v88, v221, v85
	v_fmac_f32_e32 v89, v220, v85
	v_fmac_f32_e32 v86, v219, v85
	v_fmac_f32_e32 v87, v218, v85
	v_fmac_f32_e32 v84, v217, v85
	v_fma_f32 v85, v216, v85, v247
	v_fmac_f32_e32 v170, v242, v82
	v_fmac_f32_e32 v171, v241, v82
	v_fmac_f32_e32 v104, v238, v82
	v_fmac_f32_e32 v105, v237, v82
	v_fmac_f32_e32 v102, v236, v82
	v_fmac_f32_e32 v103, v235, v82
	v_fmac_f32_e32 v100, v234, v82
	v_fmac_f32_e32 v101, v234, v83
	v_fmac_f32_e32 v106, v232, v82
	v_fmac_f32_e32 v107, v231, v82
	v_fmac_f32_e32 v96, v230, v82
	v_fmac_f32_e32 v97, v229, v82
	v_fmac_f32_e32 v94, v228, v82
	v_fmac_f32_e32 v95, v227, v82
	v_fmac_f32_e32 v92, v226, v82
	v_fmac_f32_e32 v93, v225, v82
	v_fmac_f32_e32 v90, v224, v82
	v_fmac_f32_e32 v91, v223, v82
	v_fmac_f32_e32 v88, v222, v82
	v_fmac_f32_e32 v89, v221, v82
	v_fmac_f32_e32 v86, v220, v82
	v_fmac_f32_e32 v87, v219, v82
	v_fmac_f32_e32 v84, v218, v82
	v_fmac_f32_e32 v85, v217, v82
	v_fma_f32 v82, v216, v82, v247
	v_fmac_f32_e32 v170, v243, v83
	v_fmac_f32_e32 v171, v242, v83
	v_fmac_f32_e32 v104, v239, v83
	v_fmac_f32_e32 v105, v238, v83
	v_fmac_f32_e32 v102, v237, v83
	v_fmac_f32_e32 v103, v236, v83
	v_fmac_f32_e32 v100, v235, v83
	v_fmac_f32_e32 v101, v235, v80
	v_fmac_f32_e32 v106, v233, v83
	v_fmac_f32_e32 v107, v232, v83
	v_fmac_f32_e32 v96, v231, v83
	v_fmac_f32_e32 v97, v230, v83
	v_fmac_f32_e32 v94, v229, v83
	v_fmac_f32_e32 v95, v228, v83
	v_fmac_f32_e32 v92, v227, v83
	v_fmac_f32_e32 v93, v226, v83
	v_fmac_f32_e32 v90, v225, v83
	v_fmac_f32_e32 v91, v224, v83
	v_fmac_f32_e32 v88, v223, v83
	v_fmac_f32_e32 v89, v222, v83
	v_fmac_f32_e32 v86, v221, v83
	v_fmac_f32_e32 v87, v220, v83
	v_fmac_f32_e32 v84, v219, v83
	v_fmac_f32_e32 v85, v218, v83
	v_fmac_f32_e32 v82, v217, v83
	v_fma_f32 v83, v216, v83, v247
	v_fmac_f32_e32 v170, v244, v80
	v_fmac_f32_e32 v171, v243, v80
	v_fmac_f32_e32 v104, v240, v80
	v_fmac_f32_e32 v105, v239, v80
	v_fmac_f32_e32 v102, v238, v80
	v_fmac_f32_e32 v103, v237, v80
	v_fmac_f32_e32 v100, v236, v80
	v_fmac_f32_e32 v101, v236, v81
	v_fmac_f32_e32 v106, v234, v80
	v_fmac_f32_e32 v107, v233, v80
	v_fmac_f32_e32 v96, v232, v80
	v_fmac_f32_e32 v97, v231, v80
	v_fmac_f32_e32 v94, v230, v80
	v_fmac_f32_e32 v95, v229, v80
	v_fmac_f32_e32 v92, v228, v80
	v_fmac_f32_e32 v93, v227, v80
	v_fmac_f32_e32 v90, v226, v80
	v_fmac_f32_e32 v91, v225, v80
	v_fmac_f32_e32 v88, v224, v80
	v_fmac_f32_e32 v89, v223, v80
	v_fmac_f32_e32 v86, v222, v80
	v_fmac_f32_e32 v87, v221, v80
	v_fmac_f32_e32 v84, v220, v80
	v_fmac_f32_e32 v85, v219, v80
	v_fmac_f32_e32 v82, v218, v80
	v_fmac_f32_e32 v83, v217, v80
	v_fma_f32 v80, v216, v80, v247
	v_fma_f32 v0, v216, v81, v247
	v_fmac_f32_e32 v100, v237, v81
	v_fmac_f32_e32 v101, v237, v78
	v_fmac_f32_e32 v80, v217, v81
	v_fmac_f32_e32 v0, v217, v78
	v_fmac_f32_e32 v103, v238, v81
	v_fmac_f32_e32 v100, v238, v78
	v_fmac_f32_e32 v101, v238, v79
	v_fmac_f32_e32 v83, v218, v81
	v_fmac_f32_e32 v80, v218, v78
	v_fmac_f32_e32 v0, v218, v79
	v_fmac_f32_e32 v102, v239, v81
	v_fmac_f32_e32 v103, v239, v78
	v_fmac_f32_e32 v100, v239, v79
	v_fmac_f32_e32 v101, v239, v8
	v_fmac_f32_e32 v82, v219, v81
	v_fmac_f32_e32 v83, v219, v78
	v_fmac_f32_e32 v80, v219, v79
	v_fmac_f32_e32 v0, v219, v8
	v_fmac_f32_e32 v105, v240, v81
	v_fmac_f32_e32 v102, v240, v78
	v_fmac_f32_e32 v103, v240, v79
	v_fmac_f32_e32 v100, v240, v8
	v_fmac_f32_e32 v101, v240, v9
	v_fmac_f32_e32 v97, v232, v81
	v_fmac_f32_e32 v85, v220, v81
	v_fmac_f32_e32 v82, v220, v78
	v_fmac_f32_e32 v83, v220, v79
	v_fmac_f32_e32 v80, v220, v8
	v_fmac_f32_e32 v0, v220, v9
	v_fmac_f32_e32 v104, v241, v81
	v_fmac_f32_e32 v105, v241, v78
	v_fmac_f32_e32 v102, v241, v79
	v_fmac_f32_e32 v103, v241, v8
	v_fmac_f32_e32 v100, v241, v9
	s_waitcnt lgkmcnt(5)
	v_fmac_f32_e32 v101, v241, v6
	v_fmac_f32_e32 v96, v233, v81
	v_fmac_f32_e32 v97, v233, v78
	v_fmac_f32_e32 v84, v221, v81
	v_fmac_f32_e32 v85, v221, v78
	v_fmac_f32_e32 v82, v221, v79
	v_fmac_f32_e32 v83, v221, v8
	v_fmac_f32_e32 v80, v221, v9
	v_fmac_f32_e32 v0, v221, v6
	v_fmac_f32_e32 v104, v242, v78
	v_fmac_f32_e32 v105, v242, v79
	v_fmac_f32_e32 v102, v242, v8
	v_fmac_f32_e32 v103, v242, v9
	v_fmac_f32_e32 v100, v242, v6
	v_fmac_f32_e32 v101, v242, v7
	v_fmac_f32_e32 v107, v234, v81
	v_fmac_f32_e32 v96, v234, v78
	v_fmac_f32_e32 v97, v234, v79
	v_fmac_f32_e32 v87, v222, v81
	v_fmac_f32_e32 v84, v222, v78
	v_fmac_f32_e32 v85, v222, v79
	v_fmac_f32_e32 v82, v222, v8
	v_fmac_f32_e32 v83, v222, v9
	v_fmac_f32_e32 v80, v222, v6
	v_fmac_f32_e32 v0, v222, v7
	v_fmac_f32_e32 v104, v243, v79
	v_fmac_f32_e32 v105, v243, v8
	v_fmac_f32_e32 v102, v243, v9
	v_fmac_f32_e32 v103, v243, v6
	v_fmac_f32_e32 v100, v243, v7
	s_waitcnt lgkmcnt(4)
	v_fmac_f32_e32 v101, v243, v4
	v_fmac_f32_e32 v106, v235, v81
	v_fmac_f32_e32 v107, v235, v78
	v_fmac_f32_e32 v96, v235, v79
	v_fmac_f32_e32 v97, v235, v8
	v_fmac_f32_e32 v86, v223, v81
	v_fmac_f32_e32 v87, v223, v78
	v_fmac_f32_e32 v84, v223, v79
	v_fmac_f32_e32 v85, v223, v8
	v_fmac_f32_e32 v82, v223, v9
	v_fmac_f32_e32 v83, v223, v6
	v_fmac_f32_e32 v80, v223, v7
	v_fmac_f32_e32 v0, v223, v4
	v_fmac_f32_e32 v171, v244, v81
	v_fmac_f32_e32 v104, v244, v8
	v_fmac_f32_e32 v105, v244, v9
	v_fmac_f32_e32 v102, v244, v6
	v_fmac_f32_e32 v103, v244, v7
	v_fmac_f32_e32 v100, v244, v4
	v_fmac_f32_e32 v101, v244, v5
	v_fmac_f32_e32 v106, v236, v78
	v_fmac_f32_e32 v107, v236, v79
	v_fmac_f32_e32 v96, v236, v8
	v_fmac_f32_e32 v97, v236, v9
	v_fmac_f32_e32 v89, v224, v81
	v_fmac_f32_e32 v86, v224, v78
	v_fmac_f32_e32 v87, v224, v79
	v_fmac_f32_e32 v84, v224, v8
	v_fmac_f32_e32 v85, v224, v9
	v_fmac_f32_e32 v82, v224, v6
	v_fmac_f32_e32 v83, v224, v7
	v_fmac_f32_e32 v80, v224, v4
	v_fmac_f32_e32 v0, v224, v5
	v_fmac_f32_e32 v170, v245, v81
	v_fmac_f32_e32 v171, v245, v78
	v_fmac_f32_e32 v104, v245, v9
	v_fmac_f32_e32 v105, v245, v6
	v_fmac_f32_e32 v102, v245, v7
	v_fmac_f32_e32 v103, v245, v4
	v_fmac_f32_e32 v100, v245, v5
	s_waitcnt lgkmcnt(3)
	v_fmac_f32_e32 v101, v245, v2
	v_fmac_f32_e32 v106, v237, v79
	v_fmac_f32_e32 v107, v237, v8
	v_fmac_f32_e32 v96, v237, v9
	v_fmac_f32_e32 v97, v237, v6
	v_fmac_f32_e32 v88, v225, v81
	v_fmac_f32_e32 v89, v225, v78
	v_fmac_f32_e32 v86, v225, v79
	v_fmac_f32_e32 v87, v225, v8
	v_fmac_f32_e32 v84, v225, v9
	v_fmac_f32_e32 v85, v225, v6
	v_fmac_f32_e32 v82, v225, v7
	v_fmac_f32_e32 v83, v225, v4
	v_fmac_f32_e32 v80, v225, v5
	v_fmac_f32_e32 v0, v225, v2
	v_fmac_f32_e32 v170, v246, v78
	v_fmac_f32_e32 v171, v246, v79
	v_fmac_f32_e32 v104, v246, v6
	v_fmac_f32_e32 v105, v246, v7
	v_fmac_f32_e32 v102, v246, v4
	v_fmac_f32_e32 v103, v246, v5
	v_fmac_f32_e32 v100, v246, v2
	v_fmac_f32_e32 v101, v246, v3
	v_fmac_f32_e32 v106, v238, v8
	v_fmac_f32_e32 v107, v238, v9
	v_fmac_f32_e32 v96, v238, v6
	v_fmac_f32_e32 v97, v238, v7
	v_fmac_f32_e32 v91, v226, v81
	v_fmac_f32_e32 v88, v226, v78
	v_fmac_f32_e32 v89, v226, v79
	v_fmac_f32_e32 v86, v226, v8
	v_fmac_f32_e32 v87, v226, v9
	v_fmac_f32_e32 v84, v226, v6
	v_fmac_f32_e32 v85, v226, v7
	v_fmac_f32_e32 v82, v226, v4
	v_fmac_f32_e32 v83, v226, v5
	v_fmac_f32_e32 v80, v226, v2
	v_fmac_f32_e32 v0, v226, v3
	ds_write2st64_b32 v109, v170, v171 offset0:12 offset1:18
	ds_write2st64_b32 v109, v104, v105 offset0:36 offset1:42
	ds_write2st64_b32 v109, v102, v103 offset0:48 offset1:54
	ds_write2st64_b32 v109, v100, v101 offset0:60 offset1:66
	v_fmac_f32_e32 v106, v239, v9
	v_fmac_f32_e32 v107, v239, v6
	v_fmac_f32_e32 v96, v239, v7
	v_fmac_f32_e32 v97, v239, v4
	v_fmac_f32_e32 v90, v227, v81
	v_fmac_f32_e32 v91, v227, v78
	v_fmac_f32_e32 v88, v227, v79
	v_fmac_f32_e32 v89, v227, v8
	v_fmac_f32_e32 v86, v227, v9
	v_fmac_f32_e32 v87, v227, v6
	v_fmac_f32_e32 v84, v227, v7
	v_fmac_f32_e32 v85, v227, v4
	v_fmac_f32_e32 v82, v227, v5
	v_fmac_f32_e32 v83, v227, v2
	v_fmac_f32_e32 v80, v227, v3
	s_waitcnt lgkmcnt(6)
	v_fmac_f32_e32 v0, v227, v178
	v_fmac_f32_e32 v106, v240, v6
	v_fmac_f32_e32 v107, v240, v7
	ds_read_b32 v100, v115
	ds_read_b32 v99, v116
	ds_read_b32 v98, v117
	ds_read_b32 v105, v118
	ds_read_b32 v104, v119
	ds_read_b32 v103, v120
	ds_read_b32 v102, v121
	ds_read_b32 v101, v122
	v_fmac_f32_e32 v96, v240, v4
	v_fmac_f32_e32 v97, v240, v5
	v_fmac_f32_e32 v93, v228, v81
	v_fmac_f32_e32 v90, v228, v78
	v_fmac_f32_e32 v91, v228, v79
	v_fmac_f32_e32 v88, v228, v8
	v_fmac_f32_e32 v89, v228, v9
	v_fmac_f32_e32 v86, v228, v6
	v_fmac_f32_e32 v87, v228, v7
	v_fmac_f32_e32 v84, v228, v4
	v_fmac_f32_e32 v85, v228, v5
	v_fmac_f32_e32 v82, v228, v2
	v_fmac_f32_e32 v83, v228, v3
	v_fmac_f32_e32 v80, v228, v178
	s_waitcnt lgkmcnt(7)
	v_fmac_f32_e32 v0, v228, v100
	v_fmac_f32_e32 v106, v241, v7
	v_fmac_f32_e32 v107, v241, v4
	v_fmac_f32_e32 v96, v241, v5
	v_fmac_f32_e32 v97, v241, v2
	v_fmac_f32_e32 v92, v229, v81
	v_fmac_f32_e32 v93, v229, v78
	v_fmac_f32_e32 v90, v229, v79
	v_fmac_f32_e32 v91, v229, v8
	v_fmac_f32_e32 v88, v229, v9
	v_fmac_f32_e32 v89, v229, v6
	v_fmac_f32_e32 v86, v229, v7
	v_fmac_f32_e32 v87, v229, v4
	v_fmac_f32_e32 v84, v229, v5
	v_fmac_f32_e32 v85, v229, v2
	v_fmac_f32_e32 v82, v229, v3
	v_fmac_f32_e32 v83, v229, v178
	v_fmac_f32_e32 v80, v229, v100
	s_waitcnt lgkmcnt(6)
	v_fmac_f32_e32 v0, v229, v99
	v_fmac_f32_e32 v106, v242, v4
	v_fmac_f32_e32 v107, v242, v5
	v_fmac_f32_e32 v96, v242, v2
	v_fmac_f32_e32 v97, v242, v3
	v_fmac_f32_e32 v95, v230, v81
	v_fmac_f32_e32 v92, v230, v78
	v_fmac_f32_e32 v93, v230, v79
	v_fmac_f32_e32 v90, v230, v8
	v_fmac_f32_e32 v91, v230, v9
	v_fmac_f32_e32 v88, v230, v6
	v_fmac_f32_e32 v89, v230, v7
	v_fmac_f32_e32 v86, v230, v4
	v_fmac_f32_e32 v87, v230, v5
	v_fmac_f32_e32 v84, v230, v2
	v_fmac_f32_e32 v85, v230, v3
	v_fmac_f32_e32 v82, v230, v178
	v_fmac_f32_e32 v83, v230, v100
	v_fmac_f32_e32 v80, v230, v99
	s_waitcnt lgkmcnt(5)
	v_fmac_f32_e32 v0, v230, v98
	v_fmac_f32_e32 v106, v243, v5
	v_fmac_f32_e32 v107, v243, v2
	v_fmac_f32_e32 v96, v243, v3
	v_fmac_f32_e32 v97, v243, v178
	v_fmac_f32_e32 v94, v231, v81
	v_fmac_f32_e32 v95, v231, v78
	v_fmac_f32_e32 v92, v231, v79
	v_fmac_f32_e32 v93, v231, v8
	v_fmac_f32_e32 v90, v231, v9
	v_fmac_f32_e32 v91, v231, v6
	v_fmac_f32_e32 v88, v231, v7
	v_fmac_f32_e32 v89, v231, v4
	v_fmac_f32_e32 v86, v231, v5
	v_fmac_f32_e32 v87, v231, v2
	v_fmac_f32_e32 v84, v231, v3
	v_fmac_f32_e32 v85, v231, v178
	v_fmac_f32_e32 v82, v231, v100
	v_fmac_f32_e32 v83, v231, v99
	v_fmac_f32_e32 v80, v231, v98
	s_waitcnt lgkmcnt(4)
	v_fmac_f32_e32 v0, v231, v105
	v_fmac_f32_e32 v106, v244, v2
	v_fmac_f32_e32 v107, v244, v3
	v_fmac_f32_e32 v96, v244, v178
	v_fmac_f32_e32 v97, v244, v100
	v_fmac_f32_e32 v94, v232, v78
	v_fmac_f32_e32 v95, v232, v79
	v_fmac_f32_e32 v92, v232, v8
	v_fmac_f32_e32 v93, v232, v9
	v_fmac_f32_e32 v90, v232, v6
	v_fmac_f32_e32 v91, v232, v7
	v_fmac_f32_e32 v88, v232, v4
	v_fmac_f32_e32 v89, v232, v5
	v_fmac_f32_e32 v86, v232, v2
	v_fmac_f32_e32 v87, v232, v3
	v_fmac_f32_e32 v84, v232, v178
	v_fmac_f32_e32 v85, v232, v100
	v_fmac_f32_e32 v82, v232, v99
	v_fmac_f32_e32 v83, v232, v98
	v_fmac_f32_e32 v80, v232, v105
	s_waitcnt lgkmcnt(3)
	v_fmac_f32_e32 v0, v232, v104
	v_fmac_f32_e32 v106, v245, v3
	v_fmac_f32_e32 v107, v245, v178
	v_fmac_f32_e32 v96, v245, v100
	v_fmac_f32_e32 v97, v245, v99
	v_fmac_f32_e32 v94, v233, v79
	v_fmac_f32_e32 v95, v233, v8
	v_fmac_f32_e32 v92, v233, v9
	v_fmac_f32_e32 v93, v233, v6
	v_fmac_f32_e32 v90, v233, v7
	v_fmac_f32_e32 v91, v233, v4
	v_fmac_f32_e32 v88, v233, v5
	v_fmac_f32_e32 v89, v233, v2
	v_fmac_f32_e32 v86, v233, v3
	v_fmac_f32_e32 v87, v233, v178
	v_fmac_f32_e32 v84, v233, v100
	v_fmac_f32_e32 v85, v233, v99
	v_fmac_f32_e32 v82, v233, v98
	v_fmac_f32_e32 v83, v233, v105
	v_fmac_f32_e32 v80, v233, v104
	s_waitcnt lgkmcnt(2)
	v_fmac_f32_e32 v0, v233, v103
	v_fmac_f32_e32 v106, v246, v178
	v_fmac_f32_e32 v107, v246, v100
	v_fmac_f32_e32 v96, v246, v99
	v_fmac_f32_e32 v97, v246, v98
	v_fmac_f32_e32 v94, v234, v8
	v_fmac_f32_e32 v95, v234, v9
	v_fmac_f32_e32 v92, v234, v6
	v_fmac_f32_e32 v93, v234, v7
	v_fmac_f32_e32 v90, v234, v4
	v_fmac_f32_e32 v91, v234, v5
	v_fmac_f32_e32 v88, v234, v2
	v_fmac_f32_e32 v89, v234, v3
	v_fmac_f32_e32 v86, v234, v178
	v_fmac_f32_e32 v87, v234, v100
	v_fmac_f32_e32 v84, v234, v99
	v_fmac_f32_e32 v85, v234, v98
	v_fmac_f32_e32 v82, v234, v105
	v_fmac_f32_e32 v83, v234, v104
	v_fmac_f32_e32 v80, v234, v103
	s_waitcnt lgkmcnt(1)
	v_fmac_f32_e32 v0, v234, v102
	ds_write2st64_b32 v109, v106, v107 offset0:72 offset1:78
	ds_write2st64_b32 v109, v96, v97 offset0:84 offset1:90
	v_fmac_f32_e32 v94, v235, v9
	v_fmac_f32_e32 v95, v235, v6
	v_fmac_f32_e32 v92, v235, v7
	v_fmac_f32_e32 v93, v235, v4
	v_fmac_f32_e32 v90, v235, v5
	v_fmac_f32_e32 v91, v235, v2
	v_fmac_f32_e32 v88, v235, v3
	v_fmac_f32_e32 v89, v235, v178
	v_fmac_f32_e32 v86, v235, v100
	v_fmac_f32_e32 v87, v235, v99
	v_fmac_f32_e32 v84, v235, v98
	v_fmac_f32_e32 v85, v235, v105
	v_fmac_f32_e32 v82, v235, v104
	v_fmac_f32_e32 v83, v235, v103
	v_fmac_f32_e32 v80, v235, v102
	s_waitcnt lgkmcnt(2)
	v_fmac_f32_e32 v0, v235, v101
	ds_read_b32 v185, v123
	ds_read_b32 v184, v124
	ds_read_b32 v183, v125
	ds_read_b32 v182, v126
	ds_read_b32 v181, v127
	ds_read_b32 v180, v128
	ds_read_b32 v179, v129
	ds_read_b32 v107, v130
	ds_read_b32 v106, v131
	ds_read_b32 v97, v132
	ds_read_b32 v96, v133
	v_fmac_f32_e32 v94, v236, v6
	v_fmac_f32_e32 v95, v236, v7
	v_fmac_f32_e32 v92, v236, v4
	v_fmac_f32_e32 v93, v236, v5
	v_fmac_f32_e32 v90, v236, v2
	v_fmac_f32_e32 v91, v236, v3
	v_fmac_f32_e32 v88, v236, v178
	v_fmac_f32_e32 v89, v236, v100
	v_fmac_f32_e32 v86, v236, v99
	v_fmac_f32_e32 v87, v236, v98
	v_fmac_f32_e32 v84, v236, v105
	v_fmac_f32_e32 v85, v236, v104
	v_fmac_f32_e32 v82, v236, v103
	v_fmac_f32_e32 v83, v236, v102
	v_fmac_f32_e32 v80, v236, v101
	s_waitcnt lgkmcnt(10)
	v_fmac_f32_e32 v0, v236, v185
	v_fmac_f32_e32 v94, v237, v7
	v_fmac_f32_e32 v95, v237, v4
	v_fmac_f32_e32 v92, v237, v5
	v_fmac_f32_e32 v93, v237, v2
	v_fmac_f32_e32 v90, v237, v3
	v_fmac_f32_e32 v91, v237, v178
	v_fmac_f32_e32 v88, v237, v100
	v_fmac_f32_e32 v89, v237, v99
	v_fmac_f32_e32 v86, v237, v98
	v_fmac_f32_e32 v87, v237, v105
	v_fmac_f32_e32 v84, v237, v104
	v_fmac_f32_e32 v85, v237, v103
	v_fmac_f32_e32 v82, v237, v102
	v_fmac_f32_e32 v83, v237, v101
	v_fmac_f32_e32 v80, v237, v185
	s_waitcnt lgkmcnt(9)
	v_fmac_f32_e32 v0, v237, v184
	v_fmac_f32_e32 v94, v238, v4
	v_fmac_f32_e32 v95, v238, v5
	v_fmac_f32_e32 v92, v238, v2
	v_fmac_f32_e32 v93, v238, v3
	v_fmac_f32_e32 v90, v238, v178
	v_fmac_f32_e32 v91, v238, v100
	v_fmac_f32_e32 v88, v238, v99
	v_fmac_f32_e32 v89, v238, v98
	v_fmac_f32_e32 v86, v238, v105
	v_fmac_f32_e32 v87, v238, v104
	v_fmac_f32_e32 v84, v238, v103
	v_fmac_f32_e32 v85, v238, v102
	v_fmac_f32_e32 v82, v238, v101
	v_fmac_f32_e32 v83, v238, v185
	v_fmac_f32_e32 v80, v238, v184
	s_waitcnt lgkmcnt(8)
	v_fmac_f32_e32 v0, v238, v183
	v_fmac_f32_e32 v94, v239, v5
	v_fmac_f32_e32 v95, v239, v2
	v_fmac_f32_e32 v92, v239, v3
	v_fmac_f32_e32 v93, v239, v178
	v_fmac_f32_e32 v90, v239, v100
	v_fmac_f32_e32 v91, v239, v99
	v_fmac_f32_e32 v88, v239, v98
	v_fmac_f32_e32 v89, v239, v105
	v_fmac_f32_e32 v86, v239, v104
	v_fmac_f32_e32 v87, v239, v103
	v_fmac_f32_e32 v84, v239, v102
	v_fmac_f32_e32 v85, v239, v101
	v_fmac_f32_e32 v82, v239, v185
	v_fmac_f32_e32 v83, v239, v184
	v_fmac_f32_e32 v80, v239, v183
	s_waitcnt lgkmcnt(7)
	v_fmac_f32_e32 v0, v239, v182
	v_fmac_f32_e32 v94, v240, v2
	v_fmac_f32_e32 v95, v240, v3
	v_fmac_f32_e32 v92, v240, v178
	v_fmac_f32_e32 v93, v240, v100
	v_fmac_f32_e32 v90, v240, v99
	v_fmac_f32_e32 v91, v240, v98
	v_fmac_f32_e32 v88, v240, v105
	v_fmac_f32_e32 v89, v240, v104
	v_fmac_f32_e32 v86, v240, v103
	v_fmac_f32_e32 v87, v240, v102
	v_fmac_f32_e32 v84, v240, v101
	v_fmac_f32_e32 v85, v240, v185
	v_fmac_f32_e32 v82, v240, v184
	v_fmac_f32_e32 v83, v240, v183
	v_fmac_f32_e32 v80, v240, v182
	s_waitcnt lgkmcnt(6)
	v_fmac_f32_e32 v0, v240, v181
	v_fmac_f32_e32 v94, v241, v3
	v_fmac_f32_e32 v95, v241, v178
	v_fmac_f32_e32 v92, v241, v100
	v_fmac_f32_e32 v93, v241, v99
	v_fmac_f32_e32 v90, v241, v98
	v_fmac_f32_e32 v91, v241, v105
	v_fmac_f32_e32 v88, v241, v104
	v_fmac_f32_e32 v89, v241, v103
	v_fmac_f32_e32 v86, v241, v102
	v_fmac_f32_e32 v87, v241, v101
	v_fmac_f32_e32 v84, v241, v185
	v_fmac_f32_e32 v85, v241, v184
	v_fmac_f32_e32 v82, v241, v183
	v_fmac_f32_e32 v83, v241, v182
	v_fmac_f32_e32 v80, v241, v181
	s_waitcnt lgkmcnt(5)
	v_fmac_f32_e32 v0, v241, v180
	v_fmac_f32_e32 v94, v242, v178
	v_fmac_f32_e32 v95, v242, v100
	v_fmac_f32_e32 v92, v242, v99
	v_fmac_f32_e32 v93, v242, v98
	v_fmac_f32_e32 v90, v242, v105
	v_fmac_f32_e32 v91, v242, v104
	v_fmac_f32_e32 v88, v242, v103
	v_fmac_f32_e32 v89, v242, v102
	v_fmac_f32_e32 v86, v242, v101
	v_fmac_f32_e32 v87, v242, v185
	v_fmac_f32_e32 v84, v242, v184
	v_fmac_f32_e32 v85, v242, v183
	v_fmac_f32_e32 v82, v242, v182
	v_fmac_f32_e32 v83, v242, v181
	v_fmac_f32_e32 v80, v242, v180
	s_waitcnt lgkmcnt(4)
	v_fmac_f32_e32 v0, v242, v179
	v_fmac_f32_e32 v94, v243, v100
	v_fmac_f32_e32 v95, v243, v99
	v_fmac_f32_e32 v92, v243, v98
	v_fmac_f32_e32 v93, v243, v105
	v_fmac_f32_e32 v90, v243, v104
	v_fmac_f32_e32 v91, v243, v103
	v_fmac_f32_e32 v88, v243, v102
	v_fmac_f32_e32 v89, v243, v101
	v_fmac_f32_e32 v86, v243, v185
	v_fmac_f32_e32 v87, v243, v184
	v_fmac_f32_e32 v84, v243, v183
	v_fmac_f32_e32 v85, v243, v182
	v_fmac_f32_e32 v82, v243, v181
	v_fmac_f32_e32 v83, v243, v180
	v_fmac_f32_e32 v80, v243, v179
	s_waitcnt lgkmcnt(3)
	v_fmac_f32_e32 v0, v243, v107
	v_fmac_f32_e32 v94, v244, v99
	v_fmac_f32_e32 v95, v244, v98
	v_fmac_f32_e32 v92, v244, v105
	v_fmac_f32_e32 v93, v244, v104
	v_fmac_f32_e32 v90, v244, v103
	v_fmac_f32_e32 v91, v244, v102
	v_fmac_f32_e32 v88, v244, v101
	v_fmac_f32_e32 v89, v244, v185
	v_fmac_f32_e32 v86, v244, v184
	v_fmac_f32_e32 v87, v244, v183
	v_fmac_f32_e32 v84, v244, v182
	v_fmac_f32_e32 v85, v244, v181
	v_fmac_f32_e32 v82, v244, v180
	v_fmac_f32_e32 v83, v244, v179
	v_fmac_f32_e32 v80, v244, v107
	s_waitcnt lgkmcnt(2)
	v_fmac_f32_e32 v0, v244, v106
	v_fmac_f32_e32 v94, v245, v98
	v_fmac_f32_e32 v95, v245, v105
	v_fmac_f32_e32 v92, v245, v104
	v_fmac_f32_e32 v93, v245, v103
	v_fmac_f32_e32 v90, v245, v102
	v_fmac_f32_e32 v91, v245, v101
	v_fmac_f32_e32 v88, v245, v185
	v_fmac_f32_e32 v89, v245, v184
	v_fmac_f32_e32 v86, v245, v183
	v_fmac_f32_e32 v87, v245, v182
	v_fmac_f32_e32 v84, v245, v181
	v_fmac_f32_e32 v85, v245, v180
	v_fmac_f32_e32 v82, v245, v179
	v_fmac_f32_e32 v83, v245, v107
	v_fmac_f32_e32 v80, v245, v106
	s_waitcnt lgkmcnt(1)
	v_fmac_f32_e32 v0, v245, v97
	v_fmac_f32_e32 v94, v246, v105
	v_fmac_f32_e32 v95, v246, v104
	v_fmac_f32_e32 v92, v246, v103
	v_fmac_f32_e32 v93, v246, v102
	v_fmac_f32_e32 v90, v246, v101
	v_fmac_f32_e32 v91, v246, v185
	v_fmac_f32_e32 v88, v246, v184
	v_fmac_f32_e32 v89, v246, v183
	v_fmac_f32_e32 v86, v246, v182
	v_fmac_f32_e32 v87, v246, v181
	v_fmac_f32_e32 v84, v246, v180
	v_fmac_f32_e32 v85, v246, v179
	v_fmac_f32_e32 v82, v246, v107
	v_fmac_f32_e32 v83, v246, v106
	v_fmac_f32_e32 v80, v246, v97
	s_waitcnt lgkmcnt(0)
	v_fmac_f32_e32 v0, v246, v96
	ds_write2st64_b32 v109, v94, v95 offset0:96 offset1:102
	ds_write2st64_b32 v109, v92, v93 offset0:108 offset1:114
	ds_write2st64_b32 v109, v90, v91 offset0:120 offset1:126
	ds_write2st64_b32 v109, v88, v89 offset0:132 offset1:138
	ds_write2st64_b32 v109, v86, v87 offset0:144 offset1:150
	ds_write2st64_b32 v109, v84, v85 offset0:156 offset1:162
	ds_write2st64_b32 v109, v82, v83 offset0:168 offset1:174
	ds_write2st64_b32 v109, v80, v0 offset0:180 offset1:186
	s_branch .LBB7_805
